# scan type-0 chains get the same two edits as type-1: transposed o tile stored directly, loader stage writes interleaved with next loads
# baseline (speedup 1.0000x reference)
.LBB0_503:
	s_and_b64 vcc, exec, s[8:9]
	s_cbranch_vccz .LBB0_506
	v_cvt_f32_ubyte0_e32 v0, s13
	v_sub_f32_e32 v0, 0xc0a00000, v0
	s_mov_b32 s8, 0xc2fc0000
	v_mov_b32_e32 v1, 0x42800000
	v_cmp_gt_f32_e32 vcc, s8, v0
	s_and_b64 s[14:15], vcc, exec
	s_cselect_b32 s9, 0xffffffc0, 0
	v_cndmask_b32_e32 v1, 0, v1, vcc
	v_add_f32_e32 v0, v0, v1
	v_exp_f32_e32 v0, v0
	v_mov_b32_e32 v2, v190
	v_mov_b32_e32 v113, 0
	v_ldexp_f32 v4, v0, s9
	v_sub_f32_e32 v5, 1.0, v4
	v_add_f32_e32 v0, -1.0, v5
	v_sub_f32_e32 v1, v0, v5
	v_add_f32_e32 v1, 1.0, v1
	v_sub_f32_e64 v0, -v4, v0
	v_add_f32_e32 v6, v0, v1
	v_frexp_mant_f32_e32 v7, v5
	s_mov_b32 s9, 0x3f2aaaab
	v_cvt_f64_f32_e32 v[0:1], v5
	v_frexp_exp_i32_f64_e32 v0, v[0:1]
	v_cmp_gt_f32_e32 vcc, s9, v7
	s_mov_b32 s9, 0x3f317218
	v_and_b32_e32 v3, 31, v2
	v_subbrev_co_u32_e32 v0, vcc, 0, v0, vcc
	v_sub_u32_e32 v1, 0, v0
	v_ldexp_f32 v5, v5, v1
	v_ldexp_f32 v1, v6, v1
	v_add_f32_e32 v6, -1.0, v5
	v_add_f32_e32 v9, 1.0, v5
	v_add_f32_e32 v7, 1.0, v6
	v_add_f32_e32 v10, -1.0, v9
	v_sub_f32_e32 v7, v5, v7
	v_sub_f32_e32 v5, v5, v10
	v_add_f32_e32 v7, v1, v7
	v_add_f32_e32 v1, v1, v5
	v_add_f32_e32 v5, v9, v1
	v_rcp_f32_e32 v10, v5
	v_add_f32_e32 v8, v6, v7
	v_sub_f32_e32 v6, v8, v6
	v_sub_f32_e32 v6, v7, v6
	v_sub_f32_e32 v7, v5, v9
	v_sub_f32_e32 v1, v1, v7
	v_mul_f32_e32 v7, v8, v10
	v_mul_f32_e32 v9, v5, v7
	v_fma_f32 v11, v7, v5, -v9
	v_fmac_f32_e32 v11, v7, v1
	v_add_f32_e32 v12, v9, v11
	v_sub_f32_e32 v13, v8, v12
	v_sub_f32_e32 v8, v8, v13
	v_sub_f32_e32 v9, v12, v9
	v_sub_f32_e32 v8, v8, v12
	v_add_f32_e32 v6, v6, v8
	v_sub_f32_e32 v8, v9, v11
	v_add_f32_e32 v6, v8, v6
	v_add_f32_e32 v8, v13, v6
	v_mul_f32_e32 v9, v10, v8
	v_mul_f32_e32 v11, v5, v9
	v_fma_f32 v5, v9, v5, -v11
	v_fmac_f32_e32 v5, v9, v1
	v_sub_f32_e32 v1, v13, v8
	v_add_f32_e32 v1, v6, v1
	v_add_f32_e32 v6, v11, v5
	v_sub_f32_e32 v12, v8, v6
	v_sub_f32_e32 v8, v8, v12
	v_sub_f32_e32 v11, v6, v11
	v_sub_f32_e32 v6, v8, v6
	v_add_f32_e32 v1, v1, v6
	v_sub_f32_e32 v5, v11, v5
	v_cvt_f32_i32_e32 v0, v0
	v_add_f32_e32 v1, v5, v1
	v_add_f32_e32 v5, v7, v9
	v_add_f32_e32 v1, v12, v1
	v_sub_f32_e32 v6, v5, v7
	v_mul_f32_e32 v1, v10, v1
	v_sub_f32_e32 v6, v9, v6
	v_add_f32_e32 v1, v6, v1
	v_mul_f32_e32 v9, 0x3f317218, v0
	v_add_f32_e32 v6, v5, v1
	v_fma_f32 v10, v0, s9, -v9
	v_fmamk_f32 v0, v0, 0xb102e308, v10
	v_sub_f32_e32 v5, v6, v5
	v_mul_f32_e32 v7, v6, v6
	v_mov_b32_e32 v8, 0x3ecc95a3
	v_sub_f32_e32 v1, v1, v5
	v_add_f32_e32 v5, v9, v0
	v_fmac_f32_e32 v8, 0x3e9b6dac, v7
	v_sub_f32_e32 v9, v5, v9
	v_fmaak_f32 v8, v7, v8, 0x3f2aaada
	v_sub_f32_e32 v0, v0, v9
	v_ldexp_f32 v9, v6, 1
	v_mul_f32_e32 v6, v6, v7
	v_mul_f32_e32 v6, v6, v8
	v_add_f32_e32 v7, v9, v6
	v_sub_f32_e32 v8, v7, v9
	v_ldexp_f32 v1, v1, 1
	v_sub_f32_e32 v6, v6, v8
	v_add_f32_e32 v1, v1, v6
	v_add_f32_e32 v6, v7, v1
	v_sub_f32_e32 v7, v6, v7
	v_sub_f32_e32 v1, v1, v7
	v_add_f32_e32 v7, v5, v6
	v_sub_f32_e32 v8, v7, v5
	v_sub_f32_e32 v9, v7, v8
	v_sub_f32_e32 v5, v5, v9
	v_sub_f32_e32 v6, v6, v8
	v_add_f32_e32 v5, v6, v5
	v_add_f32_e32 v6, v0, v1
	v_sub_f32_e32 v8, v6, v0
	v_sub_f32_e32 v9, v6, v8
	v_sub_f32_e32 v0, v0, v9
	v_sub_f32_e32 v1, v1, v8
	v_add_f32_e32 v0, v1, v0
	v_add_f32_e32 v1, v6, v5
	v_add_f32_e32 v5, v7, v1
	v_sub_f32_e32 v6, v5, v7
	v_sub_f32_e32 v1, v1, v6
	v_add_f32_e32 v0, v0, v1
	v_add_f32_e32 v0, v5, v0
	v_mov_b32_e32 v1, 0x7fc00000
	v_cmp_nlt_f32_e32 vcc, 1.0, v4
	s_mov_b32 s9, 0x33800000
	v_lshlrev_b32_e32 v112, 3, v3
	v_cndmask_b32_e32 v0, v1, v0, vcc
	v_mov_b32_e32 v1, 0xff800000
	v_cmp_neq_f32_e32 vcc, 1.0, v4
	s_mov_b32 s8, 0
	v_mul_u32_u24_e32 v139, 0x110, v3
	v_cndmask_b32_e32 v0, v1, v0, vcc
	v_cmp_gt_f32_e32 vcc, s9, v4
	s_lshl_b32 s9, s95, 12
	s_add_u32 s14, s16, s9
	v_cndmask_b32_e64 v0, v0, -v4, vcc
	v_mul_f32_e32 v0, 0x42800000, v0
	v_mul_f32_e32 v0, 0x3fb8aa3b, v0
	v_ashrrev_i32_e32 v4, 5, v2
	v_exp_f32_e32 v138, v0
	v_lshlrev_b32_e32 v0, 7, v4
	s_addc_u32 s15, s17, 0
	v_ashrrev_i32_e32 v1, 31, v0
	v_lshl_add_u64 v[0:1], v[0:1], 1, s[14:15]
	v_lshl_add_u64 v[114:115], v[0:1], 0, v[112:113]
	global_load_dwordx2 v[136:137], v[114:115], off
	global_load_dwordx2 v[130:131], v[114:115], off offset:512
	global_load_dwordx2 v[126:127], v[114:115], off offset:1024
	global_load_dwordx2 v[122:123], v[114:115], off offset:1536
	global_load_dwordx2 v[134:135], v[114:115], off offset:2048
	global_load_dwordx2 v[132:133], v[114:115], off offset:2560
	global_load_dwordx2 v[128:129], v[114:115], off offset:3072
	global_load_dwordx2 v[124:125], v[114:115], off offset:3584
	s_lshl_b32 s9, s13, 8
	s_add_i32 s12, s12, 0
	s_movk_i32 s13, 0x140
	s_add_i32 s12, s12, 0x1e800
	v_mul_lo_u32 v0, v4, s13
	v_lshlrev_b32_e32 v1, 1, v3
	v_add3_u32 v142, s12, v0, v1
	v_bfe_u32 v0, v2, 2, 3
	v_lshlrev_b32_e32 v1, 4, v2
	v_lshl_or_b32 v0, v4, 3, v0
	v_and_b32_e32 v1, 48, v1
	s_movk_i32 s14, 0x50
	s_waitcnt lgkmcnt(0)
	s_barrier
	s_lshl_b32 s3, s3, 23
	v_lshl_or_b32 v112, v0, 11, v1
	v_mul_lo_u32 v0, v0, s14
	s_and_b32 s13, s85, 0xc0
	v_add_u32_e32 v0, s12, v0
	s_or_b32 s3, s3, s9
	v_lshlrev_b32_e32 v140, 4, v4
	v_mul_u32_u24_e32 v141, 0x90, v3
	v_add_u32_e32 v116, 0x8000, v112
	v_mov_b32_e32 v117, v113
	v_add_u32_e32 v118, 0x10000, v112
	v_mov_b32_e32 v119, v113
	v_add_u32_e32 v120, 0x18000, v112
	v_mov_b32_e32 v121, v113
	s_or_b32 s3, s3, s13
	v_add_u32_e32 v143, v0, v1
	v_mov_b32_e32 v144, 0xe000
	v_mov_b32_e32 v0, v113
	v_mov_b32_e32 v1, v113
	v_mov_b32_e32 v2, v113
	v_mov_b32_e32 v3, v113
	v_mov_b32_e32 v4, v113
	v_mov_b32_e32 v5, v113
	v_mov_b32_e32 v6, v113
	v_mov_b32_e32 v7, v113
	v_mov_b32_e32 v8, v113
	v_mov_b32_e32 v9, v113
	v_mov_b32_e32 v10, v113
	v_mov_b32_e32 v11, v113
	v_mov_b32_e32 v12, v113
	v_mov_b32_e32 v13, v113
	v_mov_b32_e32 v14, v113
	v_mov_b32_e32 v15, v113
	v_mov_b32_e32 v16, v113
	v_mov_b32_e32 v17, v113
	v_mov_b32_e32 v18, v113
	v_mov_b32_e32 v19, v113
	v_mov_b32_e32 v20, v113
	v_mov_b32_e32 v21, v113
	v_mov_b32_e32 v22, v113
	v_mov_b32_e32 v23, v113
	v_mov_b32_e32 v24, v113
	v_mov_b32_e32 v25, v113
	v_mov_b32_e32 v26, v113
	v_mov_b32_e32 v27, v113
	v_mov_b32_e32 v28, v113
	v_mov_b32_e32 v29, v113
	v_mov_b32_e32 v30, v113
	v_mov_b32_e32 v31, v113
	v_mov_b32_e32 v32, v113
	v_mov_b32_e32 v33, v113
	v_mov_b32_e32 v34, v113
	v_mov_b32_e32 v35, v113
	v_mov_b32_e32 v36, v113
	v_mov_b32_e32 v37, v113
	v_mov_b32_e32 v38, v113
	v_mov_b32_e32 v39, v113
	v_mov_b32_e32 v40, v113
	v_mov_b32_e32 v41, v113
	v_mov_b32_e32 v42, v113
	v_mov_b32_e32 v43, v113
	v_mov_b32_e32 v44, v113
	v_mov_b32_e32 v45, v113
	v_mov_b32_e32 v46, v113
	v_mov_b32_e32 v47, v113
	v_mov_b32_e32 v48, v113
	v_mov_b32_e32 v49, v113
	v_mov_b32_e32 v50, v113
	v_mov_b32_e32 v51, v113
	v_mov_b32_e32 v52, v113
	v_mov_b32_e32 v53, v113
	v_mov_b32_e32 v54, v113
	v_mov_b32_e32 v55, v113
	v_mov_b32_e32 v56, v113
	v_mov_b32_e32 v57, v113
	v_mov_b32_e32 v58, v113
	v_mov_b32_e32 v59, v113
	v_mov_b32_e32 v60, v113
	v_mov_b32_e32 v61, v113
	v_mov_b32_e32 v62, v113
	v_mov_b32_e32 v63, v113
	v_mbcnt_lo_u32_b32 v112, -1, 0
	v_mbcnt_hi_u32_b32 v112, -1, v112
	v_lshrrev_b32_e32 v116, 5, v112
	v_and_b32_e32 v112, 31, v112
	v_lshlrev_b32_e32 v116, 4, v116
	v_lshl_or_b32 v112, v112, 11, v116
	v_add_u32_e32 v116, 0x10000, v112
.LBB0_505:
	s_bitcmp1_b32 s8, 0
	s_cselect_b32 s9, 0xf400, 0
	s_add_i32 s9, s9, 0
	v_add3_u32 v145, s9, v139, v140
	ds_read_b128 v[64:67], v145 offset:17408
	ds_read_b128 v[80:83], v145 offset:17440
	ds_read_b128 v[84:87], v145 offset:26112
	ds_read_b128 v[96:99], v145 offset:26144
	v_add3_u32 v191, s9, v141, v140
	v_cvt_pk_bf16_f32 v88, v0, v1
	v_cvt_pk_bf16_f32 v89, v2, v3
	v_cvt_pk_bf16_f32 v90, v4, v5
	v_cvt_pk_bf16_f32 v91, v6, v7
	s_waitcnt lgkmcnt(0)
	s_nop 0
	v_mfma_f32_32x32x16_bf16 v[64:79], v[88:91], v[64:67], 0
	ds_read_b128 v[92:95], v145 offset:17472
	ds_read_b128 v[100:103], v145 offset:26176
	v_cvt_pk_bf16_f32 v104, v8, v9
	v_cvt_pk_bf16_f32 v105, v10, v11
	v_cvt_pk_bf16_f32 v106, v12, v13
	v_cvt_pk_bf16_f32 v107, v14, v15
	s_nop 1
	v_mfma_f32_32x32x16_bf16 v[64:79], v[104:107], v[80:83], v[64:79]
	ds_read_b128 v[80:83], v145 offset:17504
	ds_read_b128 v[108:111], v145 offset:26208
	v_cvt_pk_bf16_f32 v146, v16, v17
	v_cvt_pk_bf16_f32 v147, v18, v19
	v_cvt_pk_bf16_f32 v148, v20, v21
	v_cvt_pk_bf16_f32 v149, v22, v23
	s_waitcnt lgkmcnt(0)
	s_nop 0
	v_mfma_f32_32x32x16_bf16 v[64:79], v[146:149], v[92:95], v[64:79]
	ds_read_b128 v[92:95], v145 offset:17536
	ds_read_b128 v[150:153], v145 offset:26240
	v_cvt_pk_bf16_f32 v154, v24, v25
	v_cvt_pk_bf16_f32 v155, v26, v27
	v_cvt_pk_bf16_f32 v156, v28, v29
	v_cvt_pk_bf16_f32 v157, v30, v31
	s_nop 1
	v_mfma_f32_32x32x16_bf16 v[64:79], v[154:157], v[80:83], v[64:79]
	ds_read_b128 v[80:83], v145 offset:17568
	ds_read_b128 v[158:161], v145 offset:26272
	v_cvt_pk_bf16_f32 v162, v32, v33
	v_cvt_pk_bf16_f32 v163, v34, v35
	v_cvt_pk_bf16_f32 v164, v36, v37
	v_cvt_pk_bf16_f32 v165, v38, v39
	s_waitcnt lgkmcnt(0)
	s_nop 0
	v_mfma_f32_32x32x16_bf16 v[64:79], v[162:165], v[92:95], v[64:79]
	ds_read_b128 v[92:95], v145 offset:17600
	ds_read_b128 v[166:169], v145 offset:26304
	v_cvt_pk_bf16_f32 v170, v40, v41
	v_cvt_pk_bf16_f32 v171, v42, v43
	v_cvt_pk_bf16_f32 v172, v44, v45
	v_cvt_pk_bf16_f32 v173, v46, v47
	s_nop 1
	v_mfma_f32_32x32x16_bf16 v[64:79], v[170:173], v[80:83], v[64:79]
	ds_read_b128 v[80:83], v145 offset:17632
	s_waitcnt vmcnt(0)
	ds_read_b128 v[174:177], v145 offset:26336
	v_cvt_pk_bf16_f32 v178, v48, v49
	v_cvt_pk_bf16_f32 v179, v50, v51
	v_cvt_pk_bf16_f32 v180, v52, v53
	v_cvt_pk_bf16_f32 v181, v54, v55
	s_waitcnt lgkmcnt(3)
	s_nop 0
	v_mfma_f32_32x32x16_bf16 v[64:79], v[178:181], v[92:95], v[64:79]
	ds_read_b128 v[182:185], v191 offset:53248
	ds_read_b128 v[186:189], v191 offset:53280
	ds_read_b128 v[192:195], v191 offset:57856
	ds_read_b128 v[196:199], v191 offset:57888
	v_cvt_pk_bf16_f32 v200, v56, v57
	v_cvt_pk_bf16_f32 v201, v58, v59
	v_cvt_pk_bf16_f32 v202, v60, v61
	v_cvt_pk_bf16_f32 v203, v62, v63
	s_waitcnt lgkmcnt(5)
	s_nop 0
	v_mfma_f32_32x32x16_bf16 v[64:79], v[200:203], v[80:83], v[64:79]
	v_mfma_f32_32x32x16_bf16 v[80:95], v[88:91], v[84:87], 0
	v_lshlrev_b32_e32 v145, 16, v136
	v_and_b32_e32 v136, 0xffff0000, v136
	v_lshlrev_b32_e32 v204, 16, v137
	v_and_b32_e32 v137, 0xffff0000, v137
	v_lshlrev_b32_e32 v205, 16, v134
	v_and_b32_e32 v134, 0xffff0000, v134
	v_lshlrev_b32_e32 v206, 16, v135
	v_mfma_f32_32x32x16_bf16 v[80:95], v[104:107], v[96:99], v[80:95]
	v_and_b32_e32 v135, 0xffff0000, v135
	v_lshlrev_b32_e32 v207, 16, v130
	v_and_b32_e32 v130, 0xffff0000, v130
	v_lshlrev_b32_e32 v208, 16, v131
	v_and_b32_e32 v131, 0xffff0000, v131
	v_lshlrev_b32_e32 v96, 16, v132
	v_and_b32_e32 v97, 0xffff0000, v132
	v_mfma_f32_32x32x16_bf16 v[80:95], v[146:149], v[100:103], v[80:95]
	v_lshlrev_b32_e32 v98, 16, v133
	v_and_b32_e32 v99, 0xffff0000, v133
	v_lshlrev_b32_e32 v104, 16, v126
	v_and_b32_e32 v105, 0xffff0000, v126
	v_lshlrev_b32_e32 v106, 16, v127
	v_and_b32_e32 v100, 0xffff0000, v127
	v_lshlrev_b32_e32 v126, 16, v128
	v_mfma_f32_32x32x16_bf16 v[80:95], v[154:157], v[108:111], v[80:95]
	v_and_b32_e32 v127, 0xffff0000, v128
	v_lshlrev_b32_e32 v128, 16, v129
	v_and_b32_e32 v129, 0xffff0000, v129
	v_lshlrev_b32_e32 v101, 16, v122
	v_and_b32_e32 v102, 0xffff0000, v122
	v_lshlrev_b32_e32 v103, 16, v123
	v_and_b32_e32 v107, 0xffff0000, v123
	v_mfma_f32_32x32x16_bf16 v[80:95], v[162:165], v[150:153], v[80:95]
	v_lshlrev_b32_e32 v122, 16, v124
	v_and_b32_e32 v123, 0xffff0000, v124
	v_lshlrev_b32_e32 v124, 16, v125
	v_and_b32_e32 v125, 0xffff0000, v125
	v_cvt_pk_bf16_f32 v108, v145, v136
	v_cvt_pk_bf16_f32 v109, v204, v137
	v_cvt_pk_bf16_f32 v110, v207, v130
	v_mfma_f32_32x32x16_bf16 v[80:95], v[170:173], v[158:161], v[80:95]
	v_cvt_pk_bf16_f32 v111, v208, v131
	v_cvt_pk_bf16_f32 v104, v104, v105
	v_cvt_pk_bf16_f32 v105, v106, v100
	v_cvt_pk_bf16_f32 v106, v101, v102
	v_cvt_pk_bf16_f32 v107, v103, v107
	v_cvt_pk_bf16_f32 v100, v205, v134
	v_cvt_pk_bf16_f32 v101, v206, v135
	v_cvt_pk_bf16_f32 v102, v96, v97
	v_cvt_pk_bf16_f32 v103, v98, v99
	v_cvt_pk_bf16_f32 v96, v126, v127
	v_cvt_pk_bf16_f32 v97, v128, v129
	v_cvt_pk_bf16_f32 v98, v122, v123
	v_cvt_pk_bf16_f32 v99, v124, v125
	v_mfma_f32_32x32x16_bf16 v[80:95], v[178:181], v[166:169], v[80:95]
	s_add_i32 s9, s8, 1
	s_cmp_lg_u32 s8, 63
	s_cselect_b32 s8, s9, 63
	v_mad_u64_u32 v[124:125], s[12:13], s8, v144, v[114:115]
	global_load_dwordx2 v[136:137], v[124:125], off
	global_load_dwordx2 v[130:131], v[124:125], off offset:512
	global_load_dwordx2 v[126:127], v[124:125], off offset:1024
	global_load_dwordx2 v[122:123], v[124:125], off offset:1536
	global_load_dwordx2 v[134:135], v[124:125], off offset:2048
	global_load_dwordx2 v[132:133], v[124:125], off offset:2560
	global_load_dwordx2 v[128:129], v[124:125], off offset:3072
	s_nop 0
	global_load_dwordx2 v[124:125], v[124:125], off offset:3584
	ds_read_b128 v[146:149], v191 offset:53312
	ds_read_b128 v[150:153], v191 offset:53344
	ds_read_b128 v[154:157], v191 offset:57920
	ds_read_b128 v[158:161], v191 offset:57952
	s_waitcnt lgkmcnt(8)
	v_mfma_f32_32x32x16_bf16 v[80:95], v[200:203], v[174:177], v[80:95]
	s_waitcnt lgkmcnt(7)
	v_mfma_f32_32x32x16_bf16 v[64:79], v[108:111], v[182:185], v[64:79]
	v_mul_f32_e32 v0, v0, v138
	v_mul_f32_e32 v1, v1, v138
	v_mul_f32_e32 v2, v2, v138
	v_mul_f32_e32 v3, v3, v138
	v_mul_f32_e32 v4, v4, v138
	v_mul_f32_e32 v5, v5, v138
	v_mul_f32_e32 v6, v6, v138
	s_waitcnt lgkmcnt(5)
	v_mfma_f32_32x32x16_bf16 v[80:95], v[108:111], v[192:195], v[80:95]
	v_mul_f32_e32 v7, v7, v138
	v_mul_f32_e32 v8, v8, v138
	v_mul_f32_e32 v9, v9, v138
	v_mul_f32_e32 v10, v10, v138
	v_mul_f32_e32 v11, v11, v138
	v_mul_f32_e32 v12, v12, v138
	v_mul_f32_e32 v13, v13, v138
	v_mul_f32_e32 v14, v14, v138
	v_mul_f32_e32 v15, v15, v138
	v_mul_f32_e32 v16, v16, v138
	v_mul_f32_e32 v17, v17, v138
	v_mul_f32_e32 v18, v18, v138
	v_mul_f32_e32 v19, v19, v138
	v_mfma_f32_32x32x16_bf16 v[64:79], v[104:107], v[186:189], v[64:79]
	v_mul_f32_e32 v20, v20, v138
	v_mul_f32_e32 v21, v21, v138
	v_mul_f32_e32 v22, v22, v138
	v_mul_f32_e32 v23, v23, v138
	v_mul_f32_e32 v24, v24, v138
	v_mul_f32_e32 v25, v25, v138
	v_mul_f32_e32 v26, v26, v138
	s_waitcnt lgkmcnt(4)
	v_mfma_f32_32x32x16_bf16 v[80:95], v[104:107], v[196:199], v[80:95]
	v_mul_f32_e32 v27, v27, v138
	v_mul_f32_e32 v28, v28, v138
	v_mul_f32_e32 v29, v29, v138
	v_mul_f32_e32 v30, v30, v138
	v_mul_f32_e32 v31, v31, v138
	ds_read_b128 v[162:165], v191 offset:34816
	ds_read_b128 v[166:169], v191 offset:39424
	ds_read_b128 v[170:173], v191 offset:44032
	ds_read_b128 v[174:177], v191 offset:48640
	s_waitcnt lgkmcnt(7)
	v_mfma_f32_32x32x16_bf16 v[64:79], v[100:103], v[146:149], v[64:79]
	v_mul_f32_e32 v32, v32, v138
	v_mul_f32_e32 v33, v33, v138
	v_mul_f32_e32 v34, v34, v138
	v_mul_f32_e32 v35, v35, v138
	v_mul_f32_e32 v36, v36, v138
	v_mul_f32_e32 v37, v37, v138
	v_mul_f32_e32 v38, v38, v138
	s_waitcnt lgkmcnt(5)
	v_mfma_f32_32x32x16_bf16 v[80:95], v[100:103], v[154:157], v[80:95]
	v_mul_f32_e32 v39, v39, v138
	v_mul_f32_e32 v40, v40, v138
	v_mul_f32_e32 v41, v41, v138
	v_mul_f32_e32 v42, v42, v138
	v_mul_f32_e32 v43, v43, v138
	v_mul_f32_e32 v44, v44, v138
	v_mul_f32_e32 v45, v45, v138
	v_mul_f32_e32 v46, v46, v138
	v_mul_f32_e32 v47, v47, v138
	v_mul_f32_e32 v48, v48, v138
	v_mul_f32_e32 v49, v49, v138
	v_mul_f32_e32 v50, v50, v138
	v_mul_f32_e32 v51, v51, v138
	v_mfma_f32_32x32x16_bf16 v[64:79], v[96:99], v[150:153], v[64:79]
	v_mul_f32_e32 v52, v52, v138
	v_mul_f32_e32 v53, v53, v138
	v_mul_f32_e32 v54, v54, v138
	v_mul_f32_e32 v55, v55, v138
	v_mul_f32_e32 v56, v56, v138
	v_mul_f32_e32 v57, v57, v138
	v_mul_f32_e32 v58, v58, v138
	s_waitcnt lgkmcnt(4)
	v_mfma_f32_32x32x16_bf16 v[80:95], v[96:99], v[158:161], v[80:95]
	v_mul_f32_e32 v59, v59, v138
	v_mul_f32_e32 v60, v60, v138
	v_mul_f32_e32 v61, v61, v138
	v_mul_f32_e32 v62, v62, v138
	v_mul_f32_e32 v63, v63, v138
	ds_read_b128 v[146:149], v191 offset:34848
	ds_read_b128 v[150:153], v191 offset:39456
	ds_read_b128 v[154:157], v191 offset:44064
	ds_read_b128 v[158:161], v191 offset:48672
	s_waitcnt lgkmcnt(7)
	v_mfma_f32_32x32x16_bf16 v[0:15], v[162:165], v[108:111], v[0:15]
	s_waitcnt lgkmcnt(5)
	v_mfma_f32_32x32x16_bf16 v[32:47], v[170:173], v[108:111], v[32:47]
	ds_read_b128 v[162:165], v191 offset:34880
	ds_read_b128 v[170:173], v191 offset:39488
	ds_read_b128 v[178:181], v191 offset:44096
	ds_read_b128 v[182:185], v191 offset:48704
	s_waitcnt lgkmcnt(7)
	v_mfma_f32_32x32x16_bf16 v[0:15], v[146:149], v[104:107], v[0:15]
	s_waitcnt lgkmcnt(5)
	v_mfma_f32_32x32x16_bf16 v[32:47], v[154:157], v[104:107], v[32:47]
	ds_read_b128 v[146:149], v191 offset:34912
	ds_read_b128 v[154:157], v191 offset:39520
	ds_read_b128 v[186:189], v191 offset:44128
	ds_read_b128 v[192:195], v191 offset:48736
	s_waitcnt lgkmcnt(7)
	v_mfma_f32_32x32x16_bf16 v[0:15], v[162:165], v[100:103], v[0:15]
	s_waitcnt lgkmcnt(5)
	v_mfma_f32_32x32x16_bf16 v[32:47], v[178:181], v[100:103], v[32:47]
	s_waitcnt lgkmcnt(3)
	v_mfma_f32_32x32x16_bf16 v[0:15], v[146:149], v[96:99], v[0:15]
	s_waitcnt lgkmcnt(1)
	v_mfma_f32_32x32x16_bf16 v[32:47], v[186:189], v[96:99], v[32:47]
	v_mfma_f32_32x32x16_bf16 v[16:31], v[166:169], v[108:111], v[16:31]
	v_cvt_pk_bf16_f32 v64, v64, v65
	v_cvt_pk_bf16_f32 v65, v66, v67
	v_cvt_pk_bf16_f32 v66, v68, v69
	v_cvt_pk_bf16_f32 v67, v70, v71
	v_cvt_pk_bf16_f32 v68, v72, v73
	v_cvt_pk_bf16_f32 v69, v74, v75
	v_cvt_pk_bf16_f32 v70, v76, v77
	v_mfma_f32_32x32x16_bf16 v[16:31], v[150:153], v[104:107], v[16:31]
	v_cvt_pk_bf16_f32 v71, v78, v79
	v_cvt_pk_bf16_f32 v72, v80, v81
	v_cvt_pk_bf16_f32 v73, v82, v83
	v_cvt_pk_bf16_f32 v74, v84, v85
	v_cvt_pk_bf16_f32 v75, v86, v87
	v_cvt_pk_bf16_f32 v76, v88, v89
	v_cvt_pk_bf16_f32 v77, v90, v91
	v_mfma_f32_32x32x16_bf16 v[16:31], v[170:173], v[100:103], v[16:31]
	v_cvt_pk_bf16_f32 v78, v92, v93
	v_cvt_pk_bf16_f32 v79, v94, v95
	v_mfma_f32_32x32x16_bf16 v[16:31], v[154:157], v[96:99], v[16:31]
	v_mfma_f32_32x32x16_bf16 v[48:63], v[174:177], v[108:111], v[48:63]
	s_nop 1
	v_permlane32_swap_b32_e32 v64, v66
	v_permlane32_swap_b32_e32 v65, v67
	v_permlane32_swap_b32_e32 v68, v70
	v_permlane32_swap_b32_e32 v69, v71
	v_permlane32_swap_b32_e32 v72, v74
	v_permlane32_swap_b32_e32 v73, v75
	v_permlane32_swap_b32_e32 v76, v78
	v_permlane32_swap_b32_e32 v77, v79
	s_ashr_i32 s8, s3, 31
	s_add_u32 s12, s80, s3
	s_addc_u32 s13, s81, s8
	v_mfma_f32_32x32x16_bf16 v[48:63], v[158:161], v[104:107], v[48:63]
	global_store_dwordx4 v112, v[64:67], s[12:13]
	global_store_dwordx4 v112, v[68:71], s[12:13] offset:32
	global_store_dwordx4 v116, v[72:75], s[12:13]
	global_store_dwordx4 v116, v[76:79], s[12:13] offset:32
	s_waitcnt lgkmcnt(0)
	s_waitcnt lgkmcnt(0)
	v_mfma_f32_32x32x16_bf16 v[48:63], v[182:185], v[100:103], v[48:63]
	s_barrier
	s_add_i32 s3, s3, 0x20000
	s_cmp_eq_u32 s9, 64
	s_mov_b32 s8, s9
	v_mfma_f32_32x32x16_bf16 v[48:63], v[192:195], v[96:99], v[48:63]
	s_cbranch_scc0 .LBB0_505

.Lpf_nopub_b1:
	s_add_i32 s0, s0, 3
	s_mul_i32 s0, s3, s0
	s_add_u32 s7, s16, s0
	s_addc_u32 s12, s17, 0
	s_add_u32 s0, s7, s14
	s_addc_u32 s1, s12, 0
	s_add_u32 s8, s7, s15
	s_addc_u32 s9, s12, 0
	s_add_u32 s60, s7, s26
	s_addc_u32 s61, s12, 0
	ds_write_b128 v112, v[0:3]
	v_lshl_add_u64 v[0:1], s[0:1], 0, v[80:81]
	global_load_dwordx4 v[0:3], v[0:1], off
	v_add_u32_e32 v145, v109, v92
	ds_write_b128 v145, v[4:7]
	v_lshl_add_u64 v[4:5], s[8:9], 0, v[80:81]
	global_load_dwordx4 v[4:7], v[4:5], off
	v_add_u32_e32 v145, v108, v94
	ds_write_b128 v145, v[8:11]
	v_lshl_add_u64 v[8:9], s[0:1], 0, v[82:83]
	global_load_dwordx4 v[8:11], v[8:9], off
	v_add_u32_e32 v145, v109, v96
	ds_write_b128 v145, v[12:15]
	v_lshl_add_u64 v[12:13], s[8:9], 0, v[82:83]
	global_load_dwordx4 v[12:15], v[12:13], off
	v_add_u32_e32 v145, v108, v98
	ds_write_b128 v145, v[16:19]
	v_lshl_add_u64 v[16:17], s[0:1], 0, v[84:85]
	global_load_dwordx4 v[16:19], v[16:17], off
	v_add_u32_e32 v145, v109, v100
	ds_write_b128 v145, v[20:23]
	v_lshl_add_u64 v[20:21], s[8:9], 0, v[84:85]
	global_load_dwordx4 v[20:23], v[20:21], off
	v_add_u32_e32 v145, v108, v102
	ds_write_b128 v145, v[24:27]
	v_lshl_add_u64 v[24:25], s[0:1], 0, v[86:87]
	global_load_dwordx4 v[24:27], v[24:25], off
	v_add_u32_e32 v145, v109, v104
	ds_write_b128 v145, v[28:31]
	v_lshl_add_u64 v[28:29], s[8:9], 0, v[86:87]
	global_load_dwordx4 v[28:31], v[28:29], off
	ds_write_b128 v110, v[32:35]
	v_lshl_add_u64 v[32:33], s[60:61], 0, v[80:81]
	global_load_dwordx4 v[32:35], v[32:33], off
	ds_write_b128 v111, v[40:43]
	v_lshl_add_u64 v[40:41], s[60:61], 0, v[88:89]
	global_load_dwordx4 v[40:43], v[40:41], off
	s_waitcnt lgkmcnt(0)
	s_barrier
	s_waitcnt vmcnt(10)
	s_cmp_eq_u32 s100, 0
	s_cbranch_scc1 .Lpf_nopub_b0
	s_mov_b64 exec, 1
	v_mov_b32_e32 v239, s6
	v_or_b32_e32 v239, 1, v239
	global_store_dword v238, v239, s[98:99]
	s_mov_b64 exec, -1
.Lpf_nopub_b0:
	s_cmp_gt_u32 s6, 61
	s_cselect_b64 s[0:1], -1, 0
	s_and_b64 vcc, exec, s[0:1]
	s_cbranch_vccnz .LBB0_516
	s_min_u32 s7, s6, 59
	s_add_i32 s7, s7, 4
	s_mul_i32 s7, s3, s7
	s_add_u32 s7, s16, s7
	s_addc_u32 s27, s17, 0
	s_add_u32 s8, s7, s14
	s_addc_u32 s9, s27, 0
	s_add_u32 s12, s7, s15
	s_addc_u32 s13, s27, 0
	s_add_u32 s60, s7, s26
	s_addc_u32 s61, s27, 0
	ds_write_b128 v91, v[36:39] offset:17408
	v_lshl_add_u64 v[36:37], s[8:9], 0, v[80:81]
	global_load_dwordx4 v[36:39], v[36:37], off
	ds_write_b128 v93, v[44:47] offset:34816
	v_lshl_add_u64 v[44:45], s[12:13], 0, v[80:81]
	global_load_dwordx4 v[44:47], v[44:45], off
	ds_write_b128 v95, v[48:51] offset:17408
	v_lshl_add_u64 v[48:49], s[8:9], 0, v[82:83]
	global_load_dwordx4 v[48:51], v[48:49], off
	ds_write_b128 v97, v[52:55] offset:34816
	v_lshl_add_u64 v[52:53], s[12:13], 0, v[82:83]
	global_load_dwordx4 v[52:55], v[52:53], off
	ds_write_b128 v99, v[56:59] offset:17408
	v_lshl_add_u64 v[56:57], s[8:9], 0, v[84:85]
	global_load_dwordx4 v[56:59], v[56:57], off
	ds_write_b128 v101, v[60:63] offset:34816
	v_lshl_add_u64 v[60:61], s[12:13], 0, v[84:85]
	global_load_dwordx4 v[60:63], v[60:61], off
	ds_write_b128 v103, v[64:67] offset:17408
	v_lshl_add_u64 v[64:65], s[8:9], 0, v[86:87]
	global_load_dwordx4 v[64:67], v[64:65], off
	ds_write_b128 v105, v[68:71] offset:34816
	v_lshl_add_u64 v[68:69], s[12:13], 0, v[86:87]
	global_load_dwordx4 v[68:71], v[68:69], off
	ds_write_b128 v106, v[72:75] offset:53248
	v_lshl_add_u64 v[72:73], s[60:61], 0, v[80:81]
	global_load_dwordx4 v[72:75], v[72:73], off
	ds_write_b128 v107, v[76:79] offset:53248
	v_lshl_add_u64 v[76:77], s[60:61], 0, v[88:89]
	global_load_dwordx4 v[76:79], v[76:77], off
	s_waitcnt lgkmcnt(0)
	s_barrier
	s_add_i32 s6, s6, 2
	s_branch .LBB0_517
